# grid barrier in the layer loop: one arrival atomic per workgroup, release detected by polling all eight group words (no top-level word / release words)
# speedup vs baseline: 1.0079x; 1.0079x over previous
.LBB0_600:
	s_andn2_saveexec_b64 s[10:11], s[10:11]
	s_cbranch_execz .LBB0_610
	s_mov_b64 s[14:15], exec
	v_readlane_b32 s4, v243, 7
	s_lshl_b32 s4, s4, 2
	v_mbcnt_lo_u32_b32 v2, s14, 0
	s_add_u32 s12, s12, s4
	v_mbcnt_hi_u32_b32 v2, s15, v2
	s_addc_u32 s13, s13, 0
	v_cmp_eq_u32_e32 vcc, 0, v2
	s_and_saveexec_b64 s[16:17], vcc
	s_cbranch_execz .LBB0_603
	s_bcnt1_i32_b64 s4, s[14:15]
	v_mov_b32_e32 v3, s4
	global_atomic_add v11, v3, s[12:13]
.LBB0_603:
	s_or_b64 exec, exec, s[16:17]
	v_readlane_b32 s4, v243, 8
	s_mul_i32 s4, s2, s4
	s_mov_b64 s[14:15], exec
	s_mov_b64 exec, 0xff
	v_mbcnt_lo_u32_b32 v2, -1, 0
	v_lshlrev_b32_e32 v3, 8, v2
	s_add_u32 s16, s8, 0xe0000
	s_addc_u32 s17, s9, 0
gbar_poll0:
	global_load_dword v2, v3, s[16:17] sc1
	s_waitcnt vmcnt(0)
	v_cmp_le_u32_e32 vcc, s4, v2
	s_nop 1
	s_cmp_eq_u32 vcc_lo, 0xff
	s_cbranch_scc1 gbar_done0
	s_sleep 1
	s_branch gbar_poll0
gbar_done0:
	s_mov_b64 exec, s[14:15]

.LBB0_615:
	s_or_b64 exec, exec, s[30:31]
	global_load_dword v22, v[30:31], off offset:1536
	global_load_dwordx2 v[20:21], v[26:27], off offset:2944
	global_load_dwordx2 v[244:245], v[26:27], off offset:2976
	global_load_dwordx2 v[246:247], v[26:27], off offset:3008
	global_load_dwordx2 v[248:249], v[26:27], off offset:3040
	v_mov_b32_e32 v137, v11
	v_mov_b32_e32 v139, v11
	v_mov_b32_e32 v141, v11
	v_mov_b32_e32 v143, v11
	s_waitcnt vmcnt(4)
	v_add_f32_e32 v17, v22, v17
	s_waitcnt vmcnt(3)
	v_lshlrev_b32_e32 v23, 16, v20
	v_and_b32_e32 v20, 0xffff0000, v20
	v_mul_f32_e32 v17, v17, v20
	v_lshlrev_b32_e32 v20, 16, v21
	v_add_f32_e32 v18, v22, v18
	v_add_f32_e32 v16, v22, v16
	v_mul_f32_e32 v18, v18, v20
	v_and_b32_e32 v20, 0xffff0000, v21
	v_add_f32_e32 v19, v22, v19
	v_mul_f32_e32 v16, v16, v23
	v_mul_f32_e32 v19, v19, v20
	v_cvt_pk_bf16_f32 v16, v16, v17
	v_cvt_pk_bf16_f32 v17, v18, v19
	v_lshl_add_u64 v[18:19], v[24:25], 0, v[136:137]
	global_store_dwordx2 v[18:19], v[16:17], off
	s_nop 0
	v_add_f32_e32 v13, v22, v13
	v_add_f32_e32 v14, v22, v14
	v_add_f32_e32 v12, v22, v12
	v_add_f32_e32 v15, v22, v15
	v_add_f32_e32 v7, v22, v7
	v_add_f32_e32 v8, v22, v8
	v_add_f32_e32 v6, v22, v6
	v_add_f32_e32 v9, v22, v9
	v_add_f32_e32 v3, v22, v3
	v_add_f32_e32 v4, v22, v4
	v_add_f32_e32 v2, v22, v2
	v_add_f32_e32 v5, v22, v5
	s_waitcnt vmcnt(2)
	v_lshlrev_b32_e32 v18, 16, v244
	v_and_b32_e32 v16, 0xffff0000, v244
	v_mul_f32_e32 v13, v13, v16
	v_lshlrev_b32_e32 v16, 16, v245
	v_mul_f32_e32 v14, v14, v16
	v_and_b32_e32 v16, 0xffff0000, v245
	v_mul_f32_e32 v12, v12, v18
	v_mul_f32_e32 v15, v15, v16
	v_cvt_pk_bf16_f32 v12, v12, v13
	v_cvt_pk_bf16_f32 v13, v14, v15
	v_lshl_add_u64 v[14:15], v[24:25], 0, v[138:139]
	global_store_dwordx2 v[14:15], v[12:13], off
	s_nop 0
	s_waitcnt vmcnt(1)
	v_lshlrev_b32_e32 v14, 16, v246
	v_and_b32_e32 v12, 0xffff0000, v246
	v_mul_f32_e32 v7, v7, v12
	v_lshlrev_b32_e32 v12, 16, v247
	v_mul_f32_e32 v8, v8, v12
	v_and_b32_e32 v12, 0xffff0000, v247
	v_mul_f32_e32 v6, v6, v14
	v_mul_f32_e32 v9, v9, v12
	v_cvt_pk_bf16_f32 v6, v6, v7
	v_cvt_pk_bf16_f32 v7, v8, v9
	v_lshl_add_u64 v[8:9], v[24:25], 0, v[140:141]
	global_store_dwordx2 v[8:9], v[6:7], off
	s_nop 0
	s_waitcnt vmcnt(0)
	v_lshlrev_b32_e32 v8, 16, v248
	v_and_b32_e32 v6, 0xffff0000, v248
	v_mul_f32_e32 v3, v3, v6
	v_lshlrev_b32_e32 v6, 16, v249
	v_mul_f32_e32 v4, v4, v6
	v_and_b32_e32 v6, 0xffff0000, v249
	v_mul_f32_e32 v2, v2, v8
	v_mul_f32_e32 v5, v5, v6
	v_cvt_pk_bf16_f32 v2, v2, v3
	v_cvt_pk_bf16_f32 v3, v4, v5
	v_lshl_add_u64 v[4:5], v[24:25], 0, v[142:143]
	global_store_dwordx2 v[4:5], v[2:3], off
	s_barrier

.LBB0_643:
	s_or_b64 exec, exec, s[30:31]
	s_lshl_b32 s2, s96, 7
	s_and_b32 s2, s2, 0x3f80
	s_or_b32 s70, s70, s2
	v_lshl_add_u64 v[20:21], s[70:71], 0, v[74:75]
	v_mov_b64_e32 v[22:23], s[62:63]
	v_mad_u64_u32 v[22:23], s[4:5], v20, s64, v[22:23]
	v_mad_i32_i24 v23, v21, s64, v23
	v_lshlrev_b64 v[20:21], 11, v[20:21]
	v_lshl_add_u64 v[20:21], s[62:63], 0, v[20:21]
	s_mov_b64 s[4:5], 0x5800400
	v_lshl_add_u64 v[24:25], v[20:21], 0, s[4:5]
	v_readlane_b32 s4, v242, 28
	v_readlane_b32 s5, v242, 29
	s_lshl_b64 s[4:5], s[4:5], 2
	s_add_u32 s4, s40, s4
	s_addc_u32 s5, s41, s5
	v_mov_b32_e32 v113, v11
	v_lshl_add_u64 v[30:31], v[74:75], 2, s[4:5]
	v_lshl_add_u64 v[20:21], v[22:23], 0, v[112:113]
	s_mov_b64 s[4:5], 0x9800000
	v_lshl_add_u64 v[26:27], v[20:21], 0, s[4:5]
	global_load_dword v32, v[30:31], off
	global_load_dwordx2 v[20:21], v[26:27], off offset:2560
	global_load_dwordx2 v[244:245], v[26:27], off offset:2592
	global_load_dwordx2 v[246:247], v[26:27], off offset:2624
	global_load_dwordx2 v[248:249], v[26:27], off offset:2656
	v_mov_b32_e32 v115, v11
	v_mov_b32_e32 v117, v11
	v_mov_b32_e32 v119, v11
	s_waitcnt vmcnt(4)
	v_add_f32_e32 v17, v32, v17
	s_waitcnt vmcnt(3)
	v_lshlrev_b32_e32 v22, 16, v20
	v_and_b32_e32 v20, 0xffff0000, v20
	v_mul_f32_e32 v17, v17, v20
	v_lshlrev_b32_e32 v20, 16, v21
	v_add_f32_e32 v18, v32, v18
	v_add_f32_e32 v16, v32, v16
	v_mul_f32_e32 v18, v18, v20
	v_and_b32_e32 v20, 0xffff0000, v21
	v_add_f32_e32 v19, v32, v19
	v_mul_f32_e32 v16, v16, v22
	v_mul_f32_e32 v19, v19, v20
	v_cvt_pk_bf16_f32 v16, v16, v17
	v_cvt_pk_bf16_f32 v17, v18, v19
	v_lshl_add_u64 v[18:19], v[24:25], 0, v[112:113]
	global_store_dwordx2 v[18:19], v[16:17], off
	s_nop 0
	v_add_f32_e32 v13, v32, v13
	v_add_f32_e32 v14, v32, v14
	v_add_f32_e32 v12, v32, v12
	v_add_f32_e32 v15, v32, v15
	v_add_f32_e32 v7, v32, v7
	v_add_f32_e32 v8, v32, v8
	v_add_f32_e32 v6, v32, v6
	v_add_f32_e32 v9, v32, v9
	v_add_f32_e32 v3, v32, v3
	v_add_f32_e32 v4, v32, v4
	v_add_f32_e32 v2, v32, v2
	v_add_f32_e32 v5, v32, v5
	s_waitcnt vmcnt(2)
	v_lshlrev_b32_e32 v18, 16, v244
	v_and_b32_e32 v16, 0xffff0000, v244
	v_mul_f32_e32 v13, v13, v16
	v_lshlrev_b32_e32 v16, 16, v245
	v_mul_f32_e32 v14, v14, v16
	v_and_b32_e32 v16, 0xffff0000, v245
	v_mul_f32_e32 v12, v12, v18
	v_mul_f32_e32 v15, v15, v16
	v_cvt_pk_bf16_f32 v12, v12, v13
	v_cvt_pk_bf16_f32 v13, v14, v15
	v_lshl_add_u64 v[14:15], v[24:25], 0, v[114:115]
	global_store_dwordx2 v[14:15], v[12:13], off
	s_nop 0
	s_waitcnt vmcnt(1)
	v_lshlrev_b32_e32 v14, 16, v246
	v_and_b32_e32 v12, 0xffff0000, v246
	v_mul_f32_e32 v7, v7, v12
	v_lshlrev_b32_e32 v12, 16, v247
	v_mul_f32_e32 v8, v8, v12
	v_and_b32_e32 v12, 0xffff0000, v247
	v_mul_f32_e32 v6, v6, v14
	v_mul_f32_e32 v9, v9, v12
	v_cvt_pk_bf16_f32 v6, v6, v7
	v_cvt_pk_bf16_f32 v7, v8, v9
	v_lshl_add_u64 v[8:9], v[24:25], 0, v[116:117]
	global_store_dwordx2 v[8:9], v[6:7], off
	s_nop 0
	s_waitcnt vmcnt(0)
	v_lshlrev_b32_e32 v8, 16, v248
	v_and_b32_e32 v6, 0xffff0000, v248
	v_mul_f32_e32 v3, v3, v6
	v_lshlrev_b32_e32 v6, 16, v249
	v_mul_f32_e32 v4, v4, v6
	v_and_b32_e32 v6, 0xffff0000, v249
	v_mul_f32_e32 v2, v2, v8
	v_mul_f32_e32 v5, v5, v6
	v_cvt_pk_bf16_f32 v2, v2, v3
	v_cvt_pk_bf16_f32 v3, v4, v5
	v_lshl_add_u64 v[4:5], v[24:25], 0, v[118:119]
	global_store_dwordx2 v[4:5], v[2:3], off
	v_mov_b32_e32 v5, 0
	v_mov_b32_e32 v4, v5
	v_mov_b32_e32 v3, v5
	v_mov_b32_e32 v2, v5
	v_mov_b32_e32 v9, v5
	v_mov_b32_e32 v8, v5
	v_mov_b32_e32 v7, v5
	v_mov_b32_e32 v6, v5
	v_mov_b32_e32 v15, v5
	v_mov_b32_e32 v14, v5
	v_mov_b32_e32 v13, v5
	v_mov_b32_e32 v12, v5
	v_mov_b32_e32 v19, v5
	v_mov_b32_e32 v18, v5
	v_mov_b32_e32 v17, v5
	v_mov_b32_e32 v16, v5
	s_and_saveexec_b64 s[30:31], s[28:29]
	s_cbranch_execz .LBB0_647
	s_mov_b64 s[4:5], 0x8000
	v_mov_b32_e32 v2, 0
	v_lshl_add_u64 v[32:33], v[28:29], 0, s[4:5]
	s_mov_b32 s48, 0
	s_mov_b64 s[34:35], 0
	v_mov_b32_e32 v34, v163
	v_mov_b32_e32 v35, v161
	v_mov_b32_e32 v3, v2
	v_mov_b32_e32 v4, v2
	v_mov_b32_e32 v5, v2
	v_mov_b32_e32 v16, v2
	v_mov_b32_e32 v17, v2
	v_mov_b32_e32 v18, v2
	v_mov_b32_e32 v19, v2
	v_mov_b32_e32 v12, v2
	v_mov_b32_e32 v13, v2
	v_mov_b32_e32 v14, v2
	v_mov_b32_e32 v15, v2
	v_mov_b32_e32 v6, v2
	v_mov_b32_e32 v7, v2
	v_mov_b32_e32 v8, v2
	v_mov_b32_e32 v9, v2

.LBB0_647:
	s_or_b64 exec, exec, s[30:31]
	global_load_dword v22, v[30:31], off offset:512
	global_load_dwordx2 v[20:21], v[26:27], off offset:2688
	global_load_dwordx2 v[244:245], v[26:27], off offset:2720
	global_load_dwordx2 v[246:247], v[26:27], off offset:2752
	global_load_dwordx2 v[248:249], v[26:27], off offset:2784
	v_mov_b32_e32 v121, v11
	v_mov_b32_e32 v123, v11
	v_mov_b32_e32 v125, v11
	v_mov_b32_e32 v127, v11
	s_waitcnt vmcnt(4)
	v_add_f32_e32 v17, v22, v17
	s_waitcnt vmcnt(3)
	v_lshlrev_b32_e32 v23, 16, v20
	v_and_b32_e32 v20, 0xffff0000, v20
	v_mul_f32_e32 v17, v17, v20
	v_lshlrev_b32_e32 v20, 16, v21
	v_add_f32_e32 v18, v22, v18
	v_add_f32_e32 v16, v22, v16
	v_mul_f32_e32 v18, v18, v20
	v_and_b32_e32 v20, 0xffff0000, v21
	v_add_f32_e32 v19, v22, v19
	v_mul_f32_e32 v16, v16, v23
	v_mul_f32_e32 v19, v19, v20
	v_cvt_pk_bf16_f32 v16, v16, v17
	v_cvt_pk_bf16_f32 v17, v18, v19
	v_lshl_add_u64 v[18:19], v[24:25], 0, v[120:121]
	global_store_dwordx2 v[18:19], v[16:17], off
	s_nop 0
	v_add_f32_e32 v13, v22, v13
	v_add_f32_e32 v14, v22, v14
	v_add_f32_e32 v12, v22, v12
	v_add_f32_e32 v15, v22, v15
	v_add_f32_e32 v7, v22, v7
	v_add_f32_e32 v8, v22, v8
	v_add_f32_e32 v6, v22, v6
	v_add_f32_e32 v9, v22, v9
	v_add_f32_e32 v3, v22, v3
	v_add_f32_e32 v4, v22, v4
	v_add_f32_e32 v2, v22, v2
	v_add_f32_e32 v5, v22, v5
	s_waitcnt vmcnt(2)
	v_lshlrev_b32_e32 v18, 16, v244
	v_and_b32_e32 v16, 0xffff0000, v244
	v_mul_f32_e32 v13, v13, v16
	v_lshlrev_b32_e32 v16, 16, v245
	v_mul_f32_e32 v14, v14, v16
	v_and_b32_e32 v16, 0xffff0000, v245
	v_mul_f32_e32 v12, v12, v18
	v_mul_f32_e32 v15, v15, v16
	v_cvt_pk_bf16_f32 v12, v12, v13
	v_cvt_pk_bf16_f32 v13, v14, v15
	v_lshl_add_u64 v[14:15], v[24:25], 0, v[122:123]
	global_store_dwordx2 v[14:15], v[12:13], off
	s_nop 0
	s_waitcnt vmcnt(1)
	v_lshlrev_b32_e32 v14, 16, v246
	v_and_b32_e32 v12, 0xffff0000, v246
	v_mul_f32_e32 v7, v7, v12
	v_lshlrev_b32_e32 v12, 16, v247
	v_mul_f32_e32 v8, v8, v12
	v_and_b32_e32 v12, 0xffff0000, v247
	v_mul_f32_e32 v6, v6, v14
	v_mul_f32_e32 v9, v9, v12
	v_cvt_pk_bf16_f32 v6, v6, v7
	v_cvt_pk_bf16_f32 v7, v8, v9
	v_lshl_add_u64 v[8:9], v[24:25], 0, v[124:125]
	global_store_dwordx2 v[8:9], v[6:7], off
	s_nop 0
	s_waitcnt vmcnt(0)
	v_lshlrev_b32_e32 v8, 16, v248
	v_and_b32_e32 v6, 0xffff0000, v248
	v_mul_f32_e32 v3, v3, v6
	v_lshlrev_b32_e32 v6, 16, v249
	v_mul_f32_e32 v4, v4, v6
	v_and_b32_e32 v6, 0xffff0000, v249
	v_mul_f32_e32 v2, v2, v8
	v_mul_f32_e32 v5, v5, v6
	v_cvt_pk_bf16_f32 v2, v2, v3
	v_cvt_pk_bf16_f32 v3, v4, v5
	v_lshl_add_u64 v[4:5], v[24:25], 0, v[126:127]
	global_store_dwordx2 v[4:5], v[2:3], off
	v_mov_b32_e32 v5, 0
	v_mov_b32_e32 v4, v5
	v_mov_b32_e32 v3, v5
	v_mov_b32_e32 v2, v5
	v_mov_b32_e32 v9, v5
	v_mov_b32_e32 v8, v5
	v_mov_b32_e32 v7, v5
	v_mov_b32_e32 v6, v5
	v_mov_b32_e32 v15, v5
	v_mov_b32_e32 v14, v5
	v_mov_b32_e32 v13, v5
	v_mov_b32_e32 v12, v5
	v_mov_b32_e32 v19, v5
	v_mov_b32_e32 v18, v5
	v_mov_b32_e32 v17, v5
	v_mov_b32_e32 v16, v5
	s_and_saveexec_b64 s[30:31], s[28:29]
	s_cbranch_execz .LBB0_651
	s_mov_b64 s[4:5], 0x10000
	v_mov_b32_e32 v2, 0
	v_lshl_add_u64 v[32:33], v[28:29], 0, s[4:5]
	s_mov_b32 s48, 0
	s_mov_b64 s[34:35], 0
	v_mov_b32_e32 v34, v164
	v_mov_b32_e32 v35, v161
	v_mov_b32_e32 v3, v2
	v_mov_b32_e32 v4, v2
	v_mov_b32_e32 v5, v2
	v_mov_b32_e32 v16, v2
	v_mov_b32_e32 v17, v2
	v_mov_b32_e32 v18, v2
	v_mov_b32_e32 v19, v2
	v_mov_b32_e32 v12, v2
	v_mov_b32_e32 v13, v2
	v_mov_b32_e32 v14, v2
	v_mov_b32_e32 v15, v2
	v_mov_b32_e32 v6, v2
	v_mov_b32_e32 v7, v2
	v_mov_b32_e32 v8, v2
	v_mov_b32_e32 v9, v2

.LBB0_651:
	s_or_b64 exec, exec, s[30:31]
	global_load_dword v22, v[30:31], off offset:1024
	global_load_dwordx2 v[20:21], v[26:27], off offset:2816
	global_load_dwordx2 v[244:245], v[26:27], off offset:2848
	global_load_dwordx2 v[246:247], v[26:27], off offset:2880
	global_load_dwordx2 v[248:249], v[26:27], off offset:2912
	v_mov_b32_e32 v129, v11
	v_mov_b32_e32 v131, v11
	v_mov_b32_e32 v133, v11
	v_mov_b32_e32 v135, v11
	s_waitcnt vmcnt(4)
	v_add_f32_e32 v17, v22, v17
	s_waitcnt vmcnt(3)
	v_lshlrev_b32_e32 v23, 16, v20
	v_and_b32_e32 v20, 0xffff0000, v20
	v_mul_f32_e32 v17, v17, v20
	v_lshlrev_b32_e32 v20, 16, v21
	v_add_f32_e32 v18, v22, v18
	v_add_f32_e32 v16, v22, v16
	v_mul_f32_e32 v18, v18, v20
	v_and_b32_e32 v20, 0xffff0000, v21
	v_add_f32_e32 v19, v22, v19
	v_mul_f32_e32 v16, v16, v23
	v_mul_f32_e32 v19, v19, v20
	v_cvt_pk_bf16_f32 v16, v16, v17
	v_cvt_pk_bf16_f32 v17, v18, v19
	v_lshl_add_u64 v[18:19], v[24:25], 0, v[128:129]
	global_store_dwordx2 v[18:19], v[16:17], off
	s_nop 0
	v_add_f32_e32 v13, v22, v13
	v_add_f32_e32 v14, v22, v14
	v_add_f32_e32 v12, v22, v12
	v_add_f32_e32 v15, v22, v15
	v_add_f32_e32 v7, v22, v7
	v_add_f32_e32 v8, v22, v8
	v_add_f32_e32 v6, v22, v6
	v_add_f32_e32 v9, v22, v9
	v_add_f32_e32 v3, v22, v3
	v_add_f32_e32 v4, v22, v4
	v_add_f32_e32 v2, v22, v2
	v_add_f32_e32 v5, v22, v5
	s_waitcnt vmcnt(2)
	v_lshlrev_b32_e32 v18, 16, v244
	v_and_b32_e32 v16, 0xffff0000, v244
	v_mul_f32_e32 v13, v13, v16
	v_lshlrev_b32_e32 v16, 16, v245
	v_mul_f32_e32 v14, v14, v16
	v_and_b32_e32 v16, 0xffff0000, v245
	v_mul_f32_e32 v12, v12, v18
	v_mul_f32_e32 v15, v15, v16
	v_cvt_pk_bf16_f32 v12, v12, v13
	v_cvt_pk_bf16_f32 v13, v14, v15
	v_lshl_add_u64 v[14:15], v[24:25], 0, v[130:131]
	global_store_dwordx2 v[14:15], v[12:13], off
	s_nop 0
	s_waitcnt vmcnt(1)
	v_lshlrev_b32_e32 v14, 16, v246
	v_and_b32_e32 v12, 0xffff0000, v246
	v_mul_f32_e32 v7, v7, v12
	v_lshlrev_b32_e32 v12, 16, v247
	v_mul_f32_e32 v8, v8, v12
	v_and_b32_e32 v12, 0xffff0000, v247
	v_mul_f32_e32 v6, v6, v14
	v_mul_f32_e32 v9, v9, v12
	v_cvt_pk_bf16_f32 v6, v6, v7
	v_cvt_pk_bf16_f32 v7, v8, v9
	v_lshl_add_u64 v[8:9], v[24:25], 0, v[132:133]
	global_store_dwordx2 v[8:9], v[6:7], off
	s_nop 0
	s_waitcnt vmcnt(0)
	v_lshlrev_b32_e32 v8, 16, v248
	v_and_b32_e32 v6, 0xffff0000, v248
	v_mul_f32_e32 v3, v3, v6
	v_lshlrev_b32_e32 v6, 16, v249
	v_mul_f32_e32 v4, v4, v6
	v_and_b32_e32 v6, 0xffff0000, v249
	v_mul_f32_e32 v2, v2, v8
	v_mul_f32_e32 v5, v5, v6
	v_cvt_pk_bf16_f32 v2, v2, v3
	v_cvt_pk_bf16_f32 v3, v4, v5
	v_lshl_add_u64 v[4:5], v[24:25], 0, v[134:135]
	global_store_dwordx2 v[4:5], v[2:3], off
	v_mov_b32_e32 v5, 0
	v_mov_b32_e32 v4, v5
	v_mov_b32_e32 v3, v5
	v_mov_b32_e32 v2, v5
	v_mov_b32_e32 v9, v5
	v_mov_b32_e32 v8, v5
	v_mov_b32_e32 v7, v5
	v_mov_b32_e32 v6, v5
	v_mov_b32_e32 v15, v5
	v_mov_b32_e32 v14, v5
	v_mov_b32_e32 v13, v5
	v_mov_b32_e32 v12, v5
	v_mov_b32_e32 v19, v5
	v_mov_b32_e32 v18, v5
	v_mov_b32_e32 v17, v5
	v_mov_b32_e32 v16, v5
	s_and_saveexec_b64 s[30:31], s[28:29]
	s_cbranch_execz .LBB0_615
	v_mov_b32_e32 v2, 0
	v_lshl_add_u64 v[28:29], v[28:29], 0, s[94:95]
	s_mov_b32 s48, 0
	s_mov_b64 s[34:35], 0
	v_mov_b32_e32 v32, v165
	v_mov_b32_e32 v33, v161
	v_mov_b32_e32 v3, v2
	v_mov_b32_e32 v4, v2
	v_mov_b32_e32 v5, v2
	v_mov_b32_e32 v16, v2
	v_mov_b32_e32 v17, v2
	v_mov_b32_e32 v18, v2
	v_mov_b32_e32 v19, v2
	v_mov_b32_e32 v12, v2
	v_mov_b32_e32 v13, v2
	v_mov_b32_e32 v14, v2
	v_mov_b32_e32 v15, v2
	v_mov_b32_e32 v6, v2
	v_mov_b32_e32 v7, v2
	v_mov_b32_e32 v8, v2
	v_mov_b32_e32 v9, v2

.LBB0_658:
	s_mov_b64 s[4:5], s[0:1]
	s_load_dwordx2 s[8:9], s[4:5], 0xd8
	s_and_b32 s4, s2, 0xff
	s_lshl_b32 s5, s2, 5
	s_and_b32 s5, s5, 0x4000
	s_lshl_b32 s6, s4, 6
	s_or_b32 s5, s6, s5
	s_mulk_i32 s5, 0x1800
	s_waitcnt lgkmcnt(0)
	s_add_u32 s5, s8, s5
	s_addc_u32 s6, s9, 0
	s_add_u32 s5, s5, 0x9800000
	s_addc_u32 s10, s6, 0
	s_cmpk_lt_u32 s2, 0x400
	s_cselect_b64 s[6:7], -1, 0
	s_and_b64 vcc, s[6:7], exec
	s_movk_i32 s6, 0x600
	s_cselect_b32 s11, s6, 0x800
	s_movk_i32 s6, 0x700
	s_cselect_b32 s6, s6, 0x900
	s_add_u32 s6, s5, s6
	s_addc_u32 s7, s10, 0
	s_lshr_b32 s12, s2, 1
	s_and_b32 s12, s12, 0x80
	s_add_u32 s6, s6, s12
	s_addc_u32 s7, s7, 0
	v_lshl_add_u64 v[28:29], s[6:7], 0, v[10:11]
	v_mov_b32_e32 v13, v11
	v_lshl_add_u64 v[30:31], v[28:29], 0, v[12:13]
	global_load_dwordx4 v[44:47], v[30:31], off
	v_mov_b32_e32 v15, v11
	v_mov_b32_e32 v17, v11
	v_mov_b32_e32 v19, v11
	v_mov_b32_e32 v21, v11
	v_mov_b32_e32 v23, v11
	v_mov_b32_e32 v25, v11
	s_add_u32 s5, s5, s11
	s_mov_b32 s6, 0xc000
	v_add_co_u32_e64 v80, s[6:7], s6, v30
	s_nop 1
	v_addc_co_u32_e64 v81, s[6:7], 0, v31, s[6:7]
	global_load_dwordx4 v[48:51], v[80:81], off
	s_mov_b32 s6, 0x18000
	v_add_co_u32_e64 v82, s[6:7], s6, v30
	s_nop 1
	v_addc_co_u32_e64 v83, s[6:7], 0, v31, s[6:7]
	global_load_dwordx4 v[52:55], v[82:83], off
	s_mov_b32 s6, 0x24000
	v_add_co_u32_e64 v84, s[6:7], s6, v30
	s_nop 1
	v_addc_co_u32_e64 v85, s[6:7], 0, v31, s[6:7]
	global_load_dwordx4 v[56:59], v[84:85], off
	s_addc_u32 s7, s10, 0
	s_add_u32 s6, s5, s12
	s_addc_u32 s7, s7, 0
	s_lshl_b32 s10, s4, 12
	v_lshl_add_u64 v[86:87], v[28:29], 0, v[14:15]
	global_load_dwordx4 v[60:63], v[86:87], off
	v_lshl_add_u64 v[88:89], v[28:29], 0, v[16:17]
	global_load_dwordx4 v[64:67], v[88:89], off
	v_lshl_add_u64 v[90:91], v[28:29], 0, v[18:19]
	global_load_dwordx4 v[68:71], v[90:91], off
	v_lshl_add_u64 v[92:93], v[28:29], 0, v[20:21]
	global_load_dwordx4 v[72:75], v[92:93], off
	v_lshl_add_u64 v[28:29], s[6:7], 0, v[22:23]
	v_lshl_add_u64 v[30:31], v[28:29], 0, v[24:25]
	s_mov_b32 s6, 0x18000
	v_add_co_u32_e64 v94, s[6:7], s6, v30
	s_nop 1
	v_addc_co_u32_e64 v95, s[6:7], 0, v31, s[6:7]
	s_mov_b32 s6, 0x30000
	v_add_co_u32_e64 v96, s[6:7], s6, v30
	s_nop 1
	v_addc_co_u32_e64 v97, s[6:7], 0, v31, s[6:7]
	v_lshlrev_b32_e32 v98, 1, v6
	v_mov_b32_e32 v99, v11
	v_lshl_add_u64 v[98:99], v[28:29], 0, v[98:99]
	global_load_dwordx4 v[104:107], v[30:31], off
	global_load_dwordx4 v[108:111], v[30:31], off offset:64
	global_load_dwordx4 v[112:115], v[94:95], off
	global_load_dwordx4 v[116:119], v[94:95], off offset:64
	global_load_dwordx4 v[120:123], v[96:97], off
	global_load_dwordx4 v[124:127], v[96:97], off offset:64
	global_load_dwordx4 v[128:131], v[98:99], off
	global_load_dwordx4 v[132:135], v[98:99], off offset:64
	s_mov_b64 s[6:7], -1
	s_waitcnt vmcnt(15)
	ds_write2_b32 v35, v44, v45 offset1:1
	ds_write2_b32 v35, v46, v47 offset0:2 offset1:3
	s_waitcnt vmcnt(14)
	v_add_u32_e32 v100, 0x420, v35
	v_add_u32_e32 v101, 0x428, v35
	ds_write2_b32 v100, v48, v49 offset1:1
	ds_write2_b32 v101, v50, v51 offset1:1
	s_waitcnt vmcnt(13)
	v_add_u32_e32 v100, 0x840, v35
	v_add_u32_e32 v101, 0x848, v35
	ds_write2_b32 v100, v52, v53 offset1:1
	ds_write2_b32 v101, v54, v55 offset1:1
	s_waitcnt vmcnt(12)
	v_add_u32_e32 v100, 0xc60, v35
	v_add_u32_e32 v101, 0xc68, v35
	ds_write2_b32 v100, v56, v57 offset1:1
	ds_write2_b32 v101, v58, v59 offset1:1
	s_waitcnt vmcnt(11)
	v_add_u32_e32 v100, 0x1080, v35
	v_add_u32_e32 v101, 0x1088, v35
	ds_write2_b32 v100, v60, v61 offset1:1
	ds_write2_b32 v101, v62, v63 offset1:1
	s_waitcnt vmcnt(10)
	v_add_u32_e32 v100, 0x14a0, v35
	v_add_u32_e32 v101, 0x14a8, v35
	ds_write2_b32 v100, v64, v65 offset1:1
	ds_write2_b32 v101, v66, v67 offset1:1
	s_waitcnt vmcnt(9)
	v_add_u32_e32 v100, 0x18c0, v35
	v_add_u32_e32 v101, 0x18c8, v35
	ds_write2_b32 v100, v68, v69 offset1:1
	ds_write2_b32 v101, v70, v71 offset1:1
	s_waitcnt vmcnt(8)
	v_add_u32_e32 v100, 0x1ce0, v35
	v_add_u32_e32 v101, 0x1ce8, v35
	ds_write2_b32 v100, v72, v73 offset1:1
	ds_write2_b32 v101, v74, v75 offset1:1
	v_add_u32_e32 v13, 0x1ce0, v35
	s_cbranch_vccnz .LBB0_660
	s_waitcnt vmcnt(0)
	s_bfe_u32 s4, s2, 0x20008
	s_lshl_b32 s4, s4, 21
	s_lshl_b32 s5, s10, 1
	s_add_u32 s4, s8, s4
	s_addc_u32 s6, s9, 0
	s_add_u32 s4, s4, s5
	s_addc_u32 s5, s6, 0
	s_add_u32 s6, s4, 0x19100000
	s_addc_u32 s7, s5, 0
	s_mov_b32 s11, 0x18000
	v_add_co_u32_e32 v38, vcc, s11, v30
	s_mov_b32 s11, 0x30000
	s_nop 0
	v_addc_co_u32_e32 v39, vcc, 0, v31, vcc
	v_mov_b32_e32 v27, v11
	v_lshl_add_u64 v[32:33], s[6:7], 0, v[26:27]
	s_nop 0
	global_store_dwordx4 v26, v[104:107], s[6:7]
	s_nop 0
	s_nop 0
	global_store_dwordx4 v26, v[108:111], s[6:7] offset:1024
	s_nop 0
	s_nop 0
	global_store_dwordx4 v26, v[112:115], s[6:7] offset:2048
	s_nop 0
	v_add_co_u32_e32 v38, vcc, s11, v30
	s_movk_i32 s11, 0x1000
	s_nop 0
	v_addc_co_u32_e32 v39, vcc, 0, v31, vcc
	v_add_co_u32_e32 v32, vcc, s11, v32
	s_nop 0
	global_store_dwordx4 v26, v[116:119], s[6:7] offset:3072
	s_nop 0
	v_addc_co_u32_e32 v33, vcc, 0, v33, vcc
	s_nop 0
	global_store_dwordx4 v36, v[120:123], s[6:7]
	s_nop 0
	s_nop 0
	global_store_dwordx4 v37, v[124:127], s[6:7]
	s_nop 1
	v_lshlrev_b32_e32 v2, 1, v6
	v_mov_b32_e32 v3, v11
	v_lshl_add_u64 v[38:39], v[28:29], 0, v[2:3]
	s_nop 0
	s_add_u32 s6, s4, 0x18100000
	s_addc_u32 s7, s5, 0
	s_nop 0
	global_store_dwordx4 v[32:33], v[128:131], off offset:2048
	s_nop 0
	s_nop 0
	global_store_dwordx4 v[32:33], v[132:135], off offset:3072
	s_waitcnt lgkmcnt(0)
	ds_read_u16 v2, v7 offset:2112
	ds_read_u16 v13, v7 offset:132
	ds_read_u16 v3, v7 offset:2244
	ds_read_u16 v15, v7 offset:264
	ds_read_u16 v4, v7 offset:2376
	ds_read_u16 v17, v7 offset:396
	ds_read_u16 v5, v7 offset:2508
	v_lshl_add_u64 v[32:33], s[6:7], 0, v[26:27]
	v_add_co_u32_e32 v32, vcc, s11, v32
	s_waitcnt lgkmcnt(0)
	v_perm_b32 v5, v5, v4, s43
	v_perm_b32 v4, v3, v2, s43
	v_perm_b32 v3, v17, v15, s43
	ds_read_u16 v2, v7
	ds_read_u16 v15, v7 offset:32
	v_addc_co_u32_e32 v33, vcc, 0, v33, vcc
	s_waitcnt lgkmcnt(1)
	v_perm_b32 v2, v13, v2, s43
	global_store_dwordx4 v26, v[2:5], s[6:7]
	ds_read_u16 v2, v7 offset:2144
	ds_read_u16 v13, v7 offset:164
	ds_read_u16 v3, v7 offset:2276
	ds_read_u16 v17, v7 offset:296
	ds_read_u16 v4, v7 offset:2408
	ds_read_u16 v19, v7 offset:428
	ds_read_u16 v5, v7 offset:2540
	s_waitcnt lgkmcnt(0)
	v_perm_b32 v5, v5, v4, s43
	v_perm_b32 v4, v3, v2, s43
	v_perm_b32 v3, v19, v17, s43
	v_perm_b32 v2, v13, v15, s43
	global_store_dwordx4 v26, v[2:5], s[6:7] offset:1024
	ds_read_u16 v2, v7 offset:2176
	ds_read_u16 v13, v7 offset:196
	ds_read_u16 v3, v7 offset:2308
	ds_read_u16 v15, v7 offset:328
	ds_read_u16 v4, v7 offset:2440
	ds_read_u16 v17, v7 offset:460
	ds_read_u16 v5, v7 offset:2572
	s_waitcnt lgkmcnt(0)
	v_perm_b32 v5, v5, v4, s43
	v_perm_b32 v4, v3, v2, s43
	v_perm_b32 v3, v17, v15, s43
	ds_read_u16 v2, v7 offset:64
	ds_read_u16 v15, v7 offset:96
	s_waitcnt lgkmcnt(1)
	v_perm_b32 v2, v13, v2, s43
	global_store_dwordx4 v26, v[2:5], s[6:7] offset:2048
	ds_read_u16 v2, v7 offset:2208
	ds_read_u16 v13, v7 offset:228
	ds_read_u16 v3, v7 offset:2340
	ds_read_u16 v17, v7 offset:360
	ds_read_u16 v4, v7 offset:2472
	ds_read_u16 v19, v7 offset:492
	ds_read_u16 v5, v7 offset:2604
	s_waitcnt lgkmcnt(0)
	v_perm_b32 v5, v5, v4, s43
	v_perm_b32 v4, v3, v2, s43
	v_perm_b32 v3, v19, v17, s43
	v_perm_b32 v2, v13, v15, s43
	global_store_dwordx4 v26, v[2:5], s[6:7] offset:3072
	ds_read_u16 v2, v7 offset:4224
	ds_read_u16 v3, v7 offset:6336
	ds_read_u16 v13, v7 offset:4356
	ds_read_u16 v4, v7 offset:6468
	ds_read_u16 v15, v7 offset:4488
	ds_read_u16 v5, v7 offset:6600
	ds_read_u16 v17, v7 offset:4620
	ds_read_u16 v19, v7 offset:6732
	s_waitcnt lgkmcnt(4)
	v_perm_b32 v4, v4, v3, s43
	v_perm_b32 v2, v13, v2, s43
	s_waitcnt lgkmcnt(1)
	v_perm_b32 v3, v17, v15, s43
	s_waitcnt lgkmcnt(0)
	v_perm_b32 v5, v19, v5, s43
	global_store_dwordx4 v36, v[2:5], s[6:7]
	ds_read_u16 v2, v7 offset:4256
	ds_read_u16 v3, v7 offset:6368
	ds_read_u16 v13, v7 offset:4388
	ds_read_u16 v4, v7 offset:6500
	ds_read_u16 v15, v7 offset:4520
	ds_read_u16 v5, v7 offset:6632
	ds_read_u16 v17, v7 offset:4652
	ds_read_u16 v19, v7 offset:6764
	s_waitcnt lgkmcnt(4)
	v_perm_b32 v4, v4, v3, s43
	v_perm_b32 v2, v13, v2, s43
	s_waitcnt lgkmcnt(1)
	v_perm_b32 v3, v17, v15, s43
	s_waitcnt lgkmcnt(0)
	v_perm_b32 v5, v19, v5, s43
	global_store_dwordx4 v37, v[2:5], s[6:7]
	ds_read_u16 v2, v7 offset:4288
	ds_read_u16 v3, v7 offset:6400
	ds_read_u16 v13, v7 offset:4420
	ds_read_u16 v4, v7 offset:6532
	ds_read_u16 v15, v7 offset:4552
	ds_read_u16 v5, v7 offset:6664
	ds_read_u16 v17, v7 offset:4684
	ds_read_u16 v19, v7 offset:6796
	s_waitcnt lgkmcnt(4)
	v_perm_b32 v4, v4, v3, s43
	v_perm_b32 v2, v13, v2, s43
	s_mov_b64 s[6:7], 0
	s_waitcnt lgkmcnt(1)
	v_perm_b32 v3, v17, v15, s43
	s_waitcnt lgkmcnt(0)
	v_perm_b32 v5, v19, v5, s43
	global_store_dwordx4 v[32:33], v[2:5], off offset:2048
	ds_read_u16 v2, v7 offset:4320
	ds_read_u16 v3, v7 offset:6432
	ds_read_u16 v13, v7 offset:4452
	ds_read_u16 v4, v7 offset:6564
	ds_read_u16 v15, v7 offset:4584
	ds_read_u16 v5, v7 offset:6696
	ds_read_u16 v17, v7 offset:4716
	ds_read_u16 v19, v7 offset:6828
	s_waitcnt lgkmcnt(4)
	v_perm_b32 v4, v4, v3, s43
	v_perm_b32 v2, v13, v2, s43
	s_waitcnt lgkmcnt(1)
	v_perm_b32 v3, v17, v15, s43
	s_waitcnt lgkmcnt(0)
	v_perm_b32 v5, v19, v5, s43
	global_store_dwordx4 v[32:33], v[2:5], off offset:3072
.LBB0_660:
	s_andn2_b64 vcc, exec, s[6:7]
	s_cbranch_vccnz .LBB0_657
	s_waitcnt vmcnt(0)
	v_mov_b32_e32 v38, v11
	v_mov_b32_e32 v39, v11
	v_mov_b32_e32 v40, v11
	s_lshr_b32 s4, s2, 8
	s_lshl_b32 s4, s4, 20
	v_mov_b32_e32 v41, v11
	s_add_u32 s4, s8, s4
	s_addc_u32 s5, s9, 0
	s_add_u32 s4, s4, s10
	s_addc_u32 s5, s5, 0
	s_nop 0
	v_lshlrev_b32_e32 v13, 16, v104
	v_and_b32_e32 v2, 0xffff0000, v104
	v_cvt_pk_fp8_f32 v38, v13, v2
	v_lshlrev_b32_e32 v15, 16, v105
	v_and_b32_e32 v3, 0xffff0000, v105
	v_lshlrev_b32_e32 v2, 16, v106
	v_cvt_pk_fp8_f32 v38, v15, v3 op_sel:[0,0,1]
	v_and_b32_e32 v3, 0xffff0000, v106
	v_cvt_pk_fp8_f32 v39, v2, v3
	v_lshlrev_b32_e32 v4, 16, v107
	v_and_b32_e32 v5, 0xffff0000, v107
	v_cvt_pk_fp8_f32 v39, v4, v5 op_sel:[0,0,1]
	s_nop 0
	s_nop 0
	v_lshlrev_b32_e32 v13, 16, v108
	v_and_b32_e32 v2, 0xffff0000, v108
	v_cvt_pk_fp8_f32 v40, v13, v2
	v_lshlrev_b32_e32 v15, 16, v109
	v_and_b32_e32 v3, 0xffff0000, v109
	v_lshlrev_b32_e32 v2, 16, v110
	v_cvt_pk_fp8_f32 v40, v15, v3 op_sel:[0,0,1]
	v_and_b32_e32 v3, 0xffff0000, v110
	v_cvt_pk_fp8_f32 v41, v2, v3
	v_lshlrev_b32_e32 v4, 16, v111
	v_and_b32_e32 v5, 0xffff0000, v111
	v_lshl_add_u64 v[2:3], s[4:5], 0, v[8:9]
	v_cvt_pk_fp8_f32 v41, v4, v5 op_sel:[0,0,1]
	s_mov_b64 s[4:5], 0x18900000
	v_lshl_add_u64 v[4:5], v[2:3], 0, s[4:5]
	s_mov_b32 s4, 0x18900000
	v_add_co_u32_e32 v32, vcc, s4, v2
	s_mov_b32 s4, 0x18000
	s_nop 0
	v_addc_co_u32_e32 v33, vcc, 0, v3, vcc
	global_store_dwordx4 v[32:33], v[38:41], off
	v_add_co_u32_e32 v32, vcc, s4, v30
	s_mov_b32 s4, 0x30000
	s_nop 0
	v_addc_co_u32_e32 v33, vcc, 0, v31, vcc
	s_nop 0
	s_nop 0
	v_lshlrev_b32_e32 v13, 16, v112
	v_and_b32_e32 v15, 0xffff0000, v112
	v_mov_b32_e32 v38, v11
	v_cvt_pk_fp8_f32 v38, v13, v15
	v_lshlrev_b32_e32 v17, 16, v113
	v_and_b32_e32 v19, 0xffff0000, v113
	v_lshlrev_b32_e32 v13, 16, v114
	v_cvt_pk_fp8_f32 v38, v17, v19 op_sel:[0,0,1]
	v_and_b32_e32 v15, 0xffff0000, v114
	v_lshlrev_b32_e32 v17, 16, v115
	v_and_b32_e32 v19, 0xffff0000, v115
	s_nop 0
	v_mov_b32_e32 v39, v11
	v_cvt_pk_fp8_f32 v39, v13, v15
	v_cvt_pk_fp8_f32 v39, v17, v19 op_sel:[0,0,1]
	s_nop 0
	v_lshlrev_b32_e32 v13, 16, v116
	v_and_b32_e32 v15, 0xffff0000, v116
	v_mov_b32_e32 v40, v11
	v_lshlrev_b32_e32 v17, 16, v117
	v_and_b32_e32 v19, 0xffff0000, v117
	v_cvt_pk_fp8_f32 v40, v13, v15
	v_lshlrev_b32_e32 v13, 16, v118
	v_and_b32_e32 v15, 0xffff0000, v118
	v_mov_b32_e32 v41, v11
	v_cvt_pk_fp8_f32 v41, v13, v15
	v_cvt_pk_fp8_f32 v40, v17, v19 op_sel:[0,0,1]
	v_lshlrev_b32_e32 v17, 16, v119
	v_and_b32_e32 v19, 0xffff0000, v119
	v_cvt_pk_fp8_f32 v41, v17, v19 op_sel:[0,0,1]
	global_store_dwordx4 v[4:5], v[38:41], off offset:1024
	s_nop 1
	v_add_co_u32_e32 v38, vcc, s4, v30
	s_mov_b64 s[4:5], 0x17900000
	s_nop 0
	v_addc_co_u32_e32 v39, vcc, 0, v31, vcc
	s_nop 0
	s_nop 0
	v_lshlrev_b32_e32 v13, 16, v120
	s_nop 0
	v_and_b32_e32 v15, 0xffff0000, v120
	v_mov_b32_e32 v30, v11
	v_cvt_pk_fp8_f32 v30, v13, v15
	v_lshlrev_b32_e32 v17, 16, v121
	v_and_b32_e32 v19, 0xffff0000, v121
	v_lshlrev_b32_e32 v13, 16, v122
	v_and_b32_e32 v15, 0xffff0000, v122
	v_mov_b32_e32 v31, v11
	v_cvt_pk_fp8_f32 v31, v13, v15
	v_mov_b32_e32 v32, v11
	v_cvt_pk_fp8_f32 v30, v17, v19 op_sel:[0,0,1]
	v_lshlrev_b32_e32 v17, 16, v123
	v_and_b32_e32 v19, 0xffff0000, v123
	v_mov_b32_e32 v33, v11
	v_cvt_pk_fp8_f32 v31, v17, v19 op_sel:[0,0,1]
	s_nop 0
	v_lshlrev_b32_e32 v13, 16, v124
	v_and_b32_e32 v15, 0xffff0000, v124
	v_cvt_pk_fp8_f32 v32, v13, v15
	v_lshlrev_b32_e32 v13, 16, v126
	v_and_b32_e32 v15, 0xffff0000, v126
	v_cvt_pk_fp8_f32 v33, v13, v15
	v_lshlrev_b32_e32 v17, 16, v125
	v_and_b32_e32 v19, 0xffff0000, v125
	v_cvt_pk_fp8_f32 v32, v17, v19 op_sel:[0,0,1]
	v_lshlrev_b32_e32 v17, 16, v127
	v_and_b32_e32 v19, 0xffff0000, v127
	v_cvt_pk_fp8_f32 v33, v17, v19 op_sel:[0,0,1]
	global_store_dwordx4 v[4:5], v[30:33], off offset:2048
	s_nop 1
	v_lshlrev_b32_e32 v30, 1, v6
	v_mov_b32_e32 v31, v11
	v_lshl_add_u64 v[32:33], v[28:29], 0, v[30:31]
	s_nop 0
	s_nop 0
	v_lshlrev_b32_e32 v13, 16, v128
	v_and_b32_e32 v15, 0xffff0000, v128
	v_mov_b32_e32 v28, v11
	v_cvt_pk_fp8_f32 v28, v13, v15
	v_lshlrev_b32_e32 v17, 16, v129
	v_and_b32_e32 v19, 0xffff0000, v129
	v_lshlrev_b32_e32 v13, 16, v130
	v_cvt_pk_fp8_f32 v28, v17, v19 op_sel:[0,0,1]
	v_and_b32_e32 v15, 0xffff0000, v130
	v_lshlrev_b32_e32 v17, 16, v131
	v_and_b32_e32 v19, 0xffff0000, v131
	s_nop 0
	v_mov_b32_e32 v29, v11
	v_cvt_pk_fp8_f32 v29, v13, v15
	v_cvt_pk_fp8_f32 v29, v17, v19 op_sel:[0,0,1]
	s_nop 0
	v_lshlrev_b32_e32 v13, 16, v132
	v_and_b32_e32 v15, 0xffff0000, v132
	v_mov_b32_e32 v30, v11
	v_lshlrev_b32_e32 v17, 16, v133
	v_and_b32_e32 v19, 0xffff0000, v133
	v_cvt_pk_fp8_f32 v30, v13, v15
	v_lshlrev_b32_e32 v13, 16, v134
	v_and_b32_e32 v15, 0xffff0000, v134
	v_mov_b32_e32 v31, v11
	v_cvt_pk_fp8_f32 v31, v13, v15
	v_cvt_pk_fp8_f32 v30, v17, v19 op_sel:[0,0,1]
	v_lshlrev_b32_e32 v17, 16, v135
	v_and_b32_e32 v19, 0xffff0000, v135
	v_cvt_pk_fp8_f32 v31, v17, v19 op_sel:[0,0,1]
	v_mov_b32_e32 v32, v11
	v_mov_b32_e32 v33, v11
	global_store_dwordx4 v[4:5], v[28:31], off offset:3072
	s_waitcnt lgkmcnt(0)
	ds_read_u16 v4, v34
	ds_read_u16 v5, v34 offset:32
	ds_read_u16 v13, v34 offset:132
	ds_read_u16 v15, v34 offset:264
	ds_read_u16 v17, v34 offset:396
	s_waitcnt lgkmcnt(4)
	v_lshlrev_b32_e32 v4, 16, v4
	v_mov_b32_e32 v30, v11
	s_waitcnt lgkmcnt(2)
	v_lshlrev_b32_e32 v13, 16, v13
	v_cvt_pk_fp8_f32 v30, v4, v13
	ds_read_u16 v4, v34 offset:2112
	ds_read_u16 v13, v34 offset:2244
	s_waitcnt lgkmcnt(3)
	v_lshlrev_b32_e32 v15, 16, v15
	s_waitcnt lgkmcnt(2)
	v_lshlrev_b32_e32 v17, 16, v17
	v_cvt_pk_fp8_f32 v30, v15, v17 op_sel:[0,0,1]
	ds_read_u16 v15, v34 offset:2376
	ds_read_u16 v17, v34 offset:2508
	s_waitcnt lgkmcnt(3)
	v_lshlrev_b32_e32 v4, 16, v4
	s_waitcnt lgkmcnt(2)
	v_lshlrev_b32_e32 v13, 16, v13
	v_mov_b32_e32 v31, v11
	v_cvt_pk_fp8_f32 v31, v4, v13
	v_lshlrev_b32_e32 v4, 16, v5
	ds_read_u16 v5, v34 offset:164
	ds_read_u16 v13, v34 offset:296
	s_waitcnt lgkmcnt(3)
	v_lshlrev_b32_e32 v15, 16, v15
	s_waitcnt lgkmcnt(2)
	v_lshlrev_b32_e32 v17, 16, v17
	v_cvt_pk_fp8_f32 v31, v15, v17 op_sel:[0,0,1]
	ds_read_u16 v15, v34 offset:428
	s_waitcnt lgkmcnt(2)
	v_lshlrev_b32_e32 v5, 16, v5
	v_cvt_pk_fp8_f32 v32, v4, v5
	ds_read_u16 v4, v34 offset:2144
	ds_read_u16 v5, v34 offset:2276
	s_waitcnt lgkmcnt(3)
	v_lshlrev_b32_e32 v13, 16, v13
	s_waitcnt lgkmcnt(2)
	v_lshlrev_b32_e32 v15, 16, v15
	v_cvt_pk_fp8_f32 v32, v13, v15 op_sel:[0,0,1]
	ds_read_u16 v13, v34 offset:2408
	ds_read_u16 v15, v34 offset:2540
	s_waitcnt lgkmcnt(3)
	v_lshlrev_b32_e32 v4, 16, v4
	s_waitcnt lgkmcnt(2)
	v_lshlrev_b32_e32 v5, 16, v5
	v_cvt_pk_fp8_f32 v33, v4, v5
	s_waitcnt lgkmcnt(1)
	v_lshlrev_b32_e32 v13, 16, v13
	s_waitcnt lgkmcnt(0)
	v_lshlrev_b32_e32 v15, 16, v15
	v_lshl_add_u64 v[28:29], v[2:3], 0, s[4:5]
	v_cvt_pk_fp8_f32 v33, v13, v15 op_sel:[0,0,1]
	s_mov_b32 s4, 0x17900000
	v_add_co_u32_e32 v2, vcc, s4, v2
	s_nop 1
	v_addc_co_u32_e32 v3, vcc, 0, v3, vcc
	global_store_dwordx4 v[2:3], v[30:33], off
	ds_read_u16 v2, v34 offset:64
	ds_read_u16 v4, v34 offset:96
	s_waitcnt lgkmcnt(1)
	v_lshlrev_b32_e32 v3, 16, v2
	ds_read_u16 v2, v34 offset:196
	s_waitcnt lgkmcnt(0)
	v_lshlrev_b32_e32 v5, 16, v2
	ds_read_u16 v2, v34 offset:328
	s_waitcnt lgkmcnt(0)
	v_lshlrev_b32_e32 v13, 16, v2
	ds_read_u16 v2, v34 offset:460
	s_waitcnt lgkmcnt(0)
	v_lshlrev_b32_e32 v15, 16, v2
	v_mov_b32_e32 v2, v11
	v_cvt_pk_fp8_f32 v2, v3, v5
	ds_read_u16 v3, v34 offset:2176
	v_cvt_pk_fp8_f32 v2, v13, v15 op_sel:[0,0,1]
	s_waitcnt lgkmcnt(0)
	v_lshlrev_b32_e32 v5, 16, v3
	ds_read_u16 v3, v34 offset:2308
	s_waitcnt lgkmcnt(0)
	v_lshlrev_b32_e32 v13, 16, v3
	ds_read_u16 v3, v34 offset:2440
	s_waitcnt lgkmcnt(0)
	v_lshlrev_b32_e32 v15, 16, v3
	ds_read_u16 v3, v34 offset:2572
	s_waitcnt lgkmcnt(0)
	v_lshlrev_b32_e32 v17, 16, v3
	v_mov_b32_e32 v3, v11
	v_cvt_pk_fp8_f32 v3, v5, v13
	v_lshlrev_b32_e32 v5, 16, v4
	ds_read_u16 v4, v34 offset:228
	v_cvt_pk_fp8_f32 v3, v15, v17 op_sel:[0,0,1]
	s_waitcnt lgkmcnt(0)
	v_lshlrev_b32_e32 v13, 16, v4
	ds_read_u16 v4, v34 offset:360
	s_waitcnt lgkmcnt(0)
	v_lshlrev_b32_e32 v15, 16, v4
	ds_read_u16 v4, v34 offset:492
	s_waitcnt lgkmcnt(0)
	v_lshlrev_b32_e32 v17, 16, v4
	v_mov_b32_e32 v4, v11
	v_cvt_pk_fp8_f32 v4, v5, v13
	ds_read_u16 v5, v34 offset:2208
	v_cvt_pk_fp8_f32 v4, v15, v17 op_sel:[0,0,1]
	s_waitcnt lgkmcnt(0)
	v_lshlrev_b32_e32 v13, 16, v5
	ds_read_u16 v5, v34 offset:2340
	s_waitcnt lgkmcnt(0)
	v_lshlrev_b32_e32 v15, 16, v5
	ds_read_u16 v5, v34 offset:2472
	s_waitcnt lgkmcnt(0)
	v_lshlrev_b32_e32 v17, 16, v5
	ds_read_u16 v5, v34 offset:2604
	s_waitcnt lgkmcnt(0)
	v_lshlrev_b32_e32 v19, 16, v5
	v_mov_b32_e32 v5, v11
	v_cvt_pk_fp8_f32 v5, v13, v15
	v_cvt_pk_fp8_f32 v5, v17, v19 op_sel:[0,0,1]
	global_store_dwordx4 v[28:29], v[2:5], off offset:1024
	ds_read_u16 v2, v34 offset:4224
	ds_read_u16 v4, v34 offset:4256
	s_waitcnt lgkmcnt(1)
	v_lshlrev_b32_e32 v3, 16, v2
	ds_read_u16 v2, v34 offset:4356
	s_waitcnt lgkmcnt(0)
	v_lshlrev_b32_e32 v5, 16, v2
	ds_read_u16 v2, v34 offset:4488
	s_waitcnt lgkmcnt(0)
	v_lshlrev_b32_e32 v13, 16, v2
	ds_read_u16 v2, v34 offset:4620
	s_waitcnt lgkmcnt(0)
	v_lshlrev_b32_e32 v15, 16, v2
	v_mov_b32_e32 v2, v11
	v_cvt_pk_fp8_f32 v2, v3, v5
	ds_read_u16 v3, v34 offset:6336
	v_cvt_pk_fp8_f32 v2, v13, v15 op_sel:[0,0,1]
	s_waitcnt lgkmcnt(0)
	v_lshlrev_b32_e32 v5, 16, v3
	ds_read_u16 v3, v34 offset:6468
	s_waitcnt lgkmcnt(0)
	v_lshlrev_b32_e32 v13, 16, v3
	ds_read_u16 v3, v34 offset:6600
	s_waitcnt lgkmcnt(0)
	v_lshlrev_b32_e32 v15, 16, v3
	ds_read_u16 v3, v34 offset:6732
	s_waitcnt lgkmcnt(0)
	v_lshlrev_b32_e32 v17, 16, v3
	v_mov_b32_e32 v3, v11
	v_cvt_pk_fp8_f32 v3, v5, v13
	v_lshlrev_b32_e32 v5, 16, v4
	ds_read_u16 v4, v34 offset:4388
	v_cvt_pk_fp8_f32 v3, v15, v17 op_sel:[0,0,1]
	s_waitcnt lgkmcnt(0)
	v_lshlrev_b32_e32 v13, 16, v4
	ds_read_u16 v4, v34 offset:4520
	s_waitcnt lgkmcnt(0)
	v_lshlrev_b32_e32 v15, 16, v4
	ds_read_u16 v4, v34 offset:4652
	s_waitcnt lgkmcnt(0)
	v_lshlrev_b32_e32 v17, 16, v4
	v_mov_b32_e32 v4, v11
	v_cvt_pk_fp8_f32 v4, v5, v13
	ds_read_u16 v5, v34 offset:6368
	v_cvt_pk_fp8_f32 v4, v15, v17 op_sel:[0,0,1]
	s_waitcnt lgkmcnt(0)
	v_lshlrev_b32_e32 v13, 16, v5
	ds_read_u16 v5, v34 offset:6500
	s_waitcnt lgkmcnt(0)
	v_lshlrev_b32_e32 v15, 16, v5
	ds_read_u16 v5, v34 offset:6632
	s_waitcnt lgkmcnt(0)
	v_lshlrev_b32_e32 v17, 16, v5
	ds_read_u16 v5, v34 offset:6764
	s_waitcnt lgkmcnt(0)
	v_lshlrev_b32_e32 v19, 16, v5
	v_mov_b32_e32 v5, v11
	v_cvt_pk_fp8_f32 v5, v13, v15
	v_cvt_pk_fp8_f32 v5, v17, v19 op_sel:[0,0,1]
	global_store_dwordx4 v[28:29], v[2:5], off offset:2048
	ds_read_u16 v2, v34 offset:4288
	ds_read_u16 v4, v34 offset:4320
	s_waitcnt lgkmcnt(1)
	v_lshlrev_b32_e32 v3, 16, v2
	ds_read_u16 v2, v34 offset:4420
	s_waitcnt lgkmcnt(0)
	v_lshlrev_b32_e32 v5, 16, v2
	ds_read_u16 v2, v34 offset:4552
	s_waitcnt lgkmcnt(0)
	v_lshlrev_b32_e32 v13, 16, v2
	ds_read_u16 v2, v34 offset:4684
	s_waitcnt lgkmcnt(0)
	v_lshlrev_b32_e32 v15, 16, v2
	v_mov_b32_e32 v2, v11
	v_cvt_pk_fp8_f32 v2, v3, v5
	ds_read_u16 v3, v34 offset:6400
	v_cvt_pk_fp8_f32 v2, v13, v15 op_sel:[0,0,1]
	s_waitcnt lgkmcnt(0)
	v_lshlrev_b32_e32 v5, 16, v3
	ds_read_u16 v3, v34 offset:6532
	s_waitcnt lgkmcnt(0)
	v_lshlrev_b32_e32 v13, 16, v3
	ds_read_u16 v3, v34 offset:6664
	s_waitcnt lgkmcnt(0)
	v_lshlrev_b32_e32 v15, 16, v3
	ds_read_u16 v3, v34 offset:6796
	s_waitcnt lgkmcnt(0)
	v_lshlrev_b32_e32 v17, 16, v3
	v_mov_b32_e32 v3, v11
	v_cvt_pk_fp8_f32 v3, v5, v13
	v_lshlrev_b32_e32 v5, 16, v4
	ds_read_u16 v4, v34 offset:4452
	v_cvt_pk_fp8_f32 v3, v15, v17 op_sel:[0,0,1]
	s_waitcnt lgkmcnt(0)
	v_lshlrev_b32_e32 v13, 16, v4
	ds_read_u16 v4, v34 offset:4584
	s_waitcnt lgkmcnt(0)
	v_lshlrev_b32_e32 v15, 16, v4
	ds_read_u16 v4, v34 offset:4716
	s_waitcnt lgkmcnt(0)
	v_lshlrev_b32_e32 v17, 16, v4
	v_mov_b32_e32 v4, v11
	v_cvt_pk_fp8_f32 v4, v5, v13
	ds_read_u16 v5, v34 offset:6432
	v_cvt_pk_fp8_f32 v4, v15, v17 op_sel:[0,0,1]
	s_waitcnt lgkmcnt(0)
	v_lshlrev_b32_e32 v17, 16, v5
	ds_read_u16 v5, v34 offset:6564
	s_waitcnt lgkmcnt(0)
	v_lshlrev_b32_e32 v19, 16, v5
	ds_read_u16 v5, v34 offset:6696
	s_waitcnt lgkmcnt(0)
	v_lshlrev_b32_e32 v13, 16, v5
	ds_read_u16 v5, v34 offset:6828
	s_waitcnt lgkmcnt(0)
	v_lshlrev_b32_e32 v15, 16, v5
	v_mov_b32_e32 v5, v11
	v_cvt_pk_fp8_f32 v5, v17, v19
	v_cvt_pk_fp8_f32 v5, v13, v15 op_sel:[0,0,1]
	global_store_dwordx4 v[28:29], v[2:5], off offset:3072
	s_branch .LBB0_657

gbar_poll1:
	global_load_dword v2, v3, s[16:17] sc1
	s_waitcnt vmcnt(0)
	v_cmp_le_u32_e32 vcc, s4, v2
	s_nop 1
	s_cmp_eq_u32 vcc_lo, 0xff
	s_cbranch_scc1 gbar_done1
	s_sleep 1
	s_branch gbar_poll1
gbar_done1:
	s_mov_b64 exec, s[14:15]

gbar_poll2:
	global_load_dword v2, v3, s[16:17] sc1
	s_waitcnt vmcnt(0)
	v_cmp_le_u32_e32 vcc, s4, v2
	s_nop 1
	s_cmp_eq_u32 vcc_lo, 0xff
	s_cbranch_scc1 gbar_done2
	s_sleep 1
	s_branch gbar_poll2
gbar_done2:
	s_mov_b64 exec, s[14:15]

gbar_poll3:
	global_load_dword v2, v3, s[16:17] sc1
	s_waitcnt vmcnt(0)
	v_cmp_le_u32_e32 vcc, s4, v2
	s_nop 1
	s_cmp_eq_u32 vcc_lo, 0xff
	s_cbranch_scc1 gbar_done3
	s_sleep 1
	s_branch gbar_poll3
gbar_done3:
	s_mov_b64 exec, s[14:15]

.LBB0_2415:
	s_andn2_saveexec_b64 s[8:9], s[8:9]
	s_cbranch_execz .LBB0_2425
	s_mov_b64 s[12:13], exec
	v_readlane_b32 s14, v243, 7
	s_lshl_b32 s14, s14, 2
	v_mbcnt_lo_u32_b32 v2, s12, 0
	s_add_u32 s10, s10, s14
	v_mbcnt_hi_u32_b32 v2, s13, v2
	s_addc_u32 s11, s11, 0
	v_cmp_eq_u32_e32 vcc, 0, v2
	s_and_saveexec_b64 s[14:15], vcc
	s_cbranch_execz .LBB0_2418
	s_bcnt1_i32_b64 s12, s[12:13]
	v_mov_b32_e32 v3, s12
	global_atomic_add v11, v3, s[10:11]
.LBB0_2418:
	s_or_b64 exec, exec, s[14:15]
	v_readlane_b32 s12, v243, 8
	s_mul_i32 s12, s38, s12
	s_mov_b64 s[14:15], exec
	s_mov_b64 exec, 0xff
	v_mbcnt_lo_u32_b32 v2, -1, 0
	v_lshlrev_b32_e32 v3, 8, v2
	s_add_u32 s16, s6, 0xe0000
	s_addc_u32 s17, s7, 0
gbar_poll4:
	global_load_dword v2, v3, s[16:17] sc1
	s_waitcnt vmcnt(0)
	v_cmp_le_u32_e32 vcc, s12, v2
	s_nop 1
	s_cmp_eq_u32 vcc_lo, 0xff
	s_cbranch_scc1 gbar_done4
	s_sleep 1
	s_branch gbar_poll4
gbar_done4:
	s_mov_b64 exec, s[14:15]

.LBB0_2456:
	s_mov_b64 s[12:13], exec
	v_readlane_b32 s2, v243, 7
	s_lshl_b32 s2, s2, 2
	v_mbcnt_lo_u32_b32 v2, s12, 0
	s_add_u32 s10, s10, s2
	v_mbcnt_hi_u32_b32 v2, s13, v2
	s_addc_u32 s11, s11, 0
	v_cmp_eq_u32_e32 vcc, 0, v2
	s_and_saveexec_b64 s[14:15], vcc
	s_cbranch_execz .LBB0_2458
	s_bcnt1_i32_b64 s2, s[12:13]
	v_mov_b32_e32 v3, s2
	global_atomic_add v11, v3, s[10:11]
.LBB0_2458:
	s_or_b64 exec, exec, s[14:15]
	v_readlane_b32 s2, v243, 8
	s_mul_i32 s2, s38, s2
	s_mov_b64 s[14:15], exec
	s_mov_b64 exec, 0xff
	v_mbcnt_lo_u32_b32 v2, -1, 0
	v_lshlrev_b32_e32 v3, 8, v2
	s_add_u32 s16, s6, 0xe0000
	s_addc_u32 s17, s7, 0
gbar_poll5:
	global_load_dword v2, v3, s[16:17] sc1
	s_waitcnt vmcnt(0)
	v_cmp_le_u32_e32 vcc, s2, v2
	s_nop 1
	s_cmp_eq_u32 vcc_lo, 0xff
	s_cbranch_scc1 gbar_done5
	s_sleep 1
	s_branch gbar_poll5
gbar_done5:
	s_mov_b64 exec, s[14:15]
	s_getpc_b64 s[98:99]
